# o20 plus s_setprio 2 for the early (critical-path) attention waves, 0 for late waves
# baseline (speedup 1.0000x reference)
; #define AT_WAIT_BAR(N) asm volatile("s_waitcnt vmcnt(" #N ") lgkmcnt(0)\n\ts_barrier" ::: "memory")
; template <int THRL>
; __device__ __forceinline__ void attn_item(int b, int h, int s, const bf16_t* Q, const bf16_t* KN, const bf16_t* KR, const bf16_t* V, const float* goa  , bf16_t* Y, float* ssqy, AT_LAS char* shm, int wid0) {
;     ...
;         for (int t = 0; t < NT; ++t) {
;             AT_WAIT_BAR(3);
;             AT_DMA(t + 3, t + 2, NT);
;             const int jb = t - (NT - 4);
;             const bool need = jb <= wq;
;             if (late) { if (have) pv(o, vp0 + ((t - 1) & 3) * VSLOTB, pw0, pw1, pw2, pw3);
;                         have = false; if (need) qkt(p0, p1, kp0 + (t & 3) * KSLOTB, qr, negm); }
.LBB13_765:
	s_min_u32 s84, s9, s5
	s_add_i32 s88, s9, -1
	s_min_u32 s92, s88, s5
	s_and_b32 s88, s84, 3
	s_and_b64 vcc, exec, s[0:1]
	s_cbranch_vccnz .Lat0_lw
	s_setprio 2
	s_waitcnt vmcnt(3) lgkmcnt(0)
	s_branch .Lat0_lwd
.Lat0_lw:
	s_setprio 0
	s_waitcnt vmcnt(2) lgkmcnt(0)

; __device__ __forceinline__ int lane_id() { int l; asm volatile("v_mbcnt_lo_u32_b32 %0, -1, 0\n\tv_mbcnt_hi_u32_b32 %0, -1, %0" : "=v"(l)); return l; }
; #define LAS __attribute__((address_space(3)))
; __device__ __forceinline__ void xb_add_l2(unsigned* p, unsigned v) { (void)__hip_atomic_fetch_add(p, v, __ATOMIC_RELAXED, __HIP_MEMORY_SCOPE_WORKGROUP); }
; __device__ __forceinline__ unsigned xb_ld_l2(unsigned* p) { unsigned v; const unsigned z = 0u; asm volatile("global_atomic_add %0, %1, %2, off sc0\n\ts_waitcnt vmcnt(0)" : "=v"(v) : "v"(p), "v"(z) : "memory"); return v; }
; __device__ __forceinline__ unsigned xb_xcc_id() { return (unsigned)__builtin_amdgcn_s_getreg((3 << 11) | 20) & 0xFu; }
; #define XB_SPIN(cond, bar) do { unsigned _sp = 0; while (cond) { __builtin_amdgcn_s_sleep(1); \
;     if ((++_sp & 255u) == 0u) { if (xb_ld(&(bar)[XB_TMO])) break; if (_sp > XB_SPIN_CAP) { atomicAdd(&(bar)[XB_TMO], 1u); break; } } } } while (0)
; #define MK_SEAM_L(k) do { if (MK_IN_(k) && MK_IN_((k) + 1)) { MK_BAR(); if (__builtin_amdgcn_readfirstlane((int)MISC[15]) != 0) xcd_local_barrier(bar.bar, bar.st, wid0); else xcd_barrier(bar, wid0); } } while (0)
; __device__ __forceinline__ void xcd_local_barrier(unsigned* bar, volatile LAS unsigned* st, int wid0) {
;     asm volatile("s_waitcnt vmcnt(0)" ::: "memory");
;     __syncthreads();
;     if (wid0 == 0 && lane_id() == 0) {
;         unsigned zo = 0; asm volatile("" : "+s"(zo));
;         unsigned* cnt = bar + zo + XB_LCNT2(xb_xcc_id());
;         const unsigned e = st[6] + 1u; st[6] = e; const unsigned target = e * st[4];
;         xb_add_l2(cnt, 1u);
;         XB_SPIN(xb_ld_l2(cnt) < target, bar);
;         __builtin_amdgcn_fence(__ATOMIC_ACQUIRE, "agent");
;         asm volatile("s_waitcnt vmcnt(0)" ::: "memory");
;     }
;     __syncthreads();
; }
; template <int l>
; __device__ __forceinline__ void layer_phases(const Args& args, LAS unsigned char* L, volatile LAS unsigned* MISC, int wid0, int lo, int hi) {
;     ...
;     MK_SEAM_L(P + 3);
.LBB13_835:
	s_setprio 0
	s_cmp_gt_i32 s89, 6
	v_readlane_b32 s0, v238, 12
	s_cselect_b64 s[2:3], -1, 0
	v_readlane_b32 s1, v238, 13
	s_and_b64 s[0:1], s[0:1], s[2:3]
	s_and_b64 vcc, exec, s[0:1]
	v_readlane_b32 s85, v238, 9
	s_cbranch_vccz .LBB13_915
	s_load_dword s4, s[86:87], 0xb8
	s_load_dwordx2 s[0:1], s[86:87], 0xa8
	s_getreg_b32 s22, hwreg(HW_REG_XCC_ID, 0, 4)
	s_waitcnt lgkmcnt(0)
	s_mulk_i32 s4, 0xd80
	s_ashr_i32 s5, s4, 31
	s_lshl_b64 s[4:5], s[4:5], 2
	s_add_u32 s0, s0, s4
	s_addc_u32 s1, s1, s5
	s_add_u32 s4, s0, 0x4000
	s_addc_u32 s5, s1, 0
	s_add_i32 s0, 0, 0x2117c
	v_mov_b32_e32 v0, s0
	ds_read_b32 v0, v0
	s_waitcnt lgkmcnt(0)
	v_readfirstlane_b32 s0, v0
	s_cmp_eq_u32 s0, 0
	s_cbranch_scc1 .LBB13_851
	s_waitcnt vmcnt(0)
	v_readlane_b32 s0, v238, 10
	v_readlane_b32 s1, v238, 11
	s_and_b64 vcc, exec, s[0:1]
	s_barrier
	s_cbranch_vccnz .LBB13_858
	v_mbcnt_lo_u32_b32 v0, -1, 0
	v_mbcnt_hi_u32_b32 v0, -1, v0
	s_mov_b32 s9, 0
	v_cmp_eq_u32_e32 vcc, 0, v0
	s_and_saveexec_b64 s[0:1], vcc
	s_cbranch_execz .LBB13_857
	s_mov_b32 s8, 0
	s_lshl_b64 s[8:9], s[8:9], 2
	s_add_u32 s8, s4, s8
	s_getreg_b32 s10, hwreg(HW_REG_XCC_ID, 0, 4)
	s_addc_u32 s9, s5, s9
	s_lshl_b32 s10, s10, 8
	s_and_b32 s10, s10, 0xf00
	s_add_u32 s8, s8, s10
	s_addc_u32 s9, s9, 0
	s_add_u32 s8, s8, 0xb200
	s_addc_u32 s9, s9, 0
	s_add_i32 s10, 0, 0x21178
	v_mov_b32_e32 v1, s10
	ds_read_b32 v0, v1
	s_add_i32 s10, 0, 0x21170
	s_mov_b64 s[6:7], exec
	s_waitcnt vmcnt(0)
	v_mbcnt_lo_u32_b32 v2, s6, 0
	v_mbcnt_hi_u32_b32 v2, s7, v2
	s_waitcnt lgkmcnt(0)
	v_add_u32_e32 v0, 1, v0
	ds_write_b32 v1, v0
	v_mov_b32_e32 v1, s10
	ds_read_b32 v1, v1
	s_mov_b32 s23, 1
	v_cmp_eq_u32_e32 vcc, 0, v2
	s_and_saveexec_b64 s[10:11], vcc
	s_cbranch_execz .LBB13_841
	s_bcnt1_i32_b64 s6, s[6:7]
	v_mov_b32_e32 v2, 0
	v_mov_b32_e32 v3, s6
	global_atomic_add v2, v3, s[8:9]

; #define AT_WAIT_BAR(N) asm volatile("s_waitcnt vmcnt(" #N ") lgkmcnt(0)\n\ts_barrier" ::: "memory")
; template <int THRL>
; __device__ __forceinline__ void attn_item(int b, int h, int s, const bf16_t* Q, const bf16_t* KN, const bf16_t* KR, const bf16_t* V, const float* goa  , bf16_t* Y, float* ssqy, AT_LAS char* shm, int wid0) {
;     ...
;         for (int t = 0; t < NT; ++t) {
;             AT_WAIT_BAR(3);
;             AT_DMA(t + 3, t + 2, NT);
;             const int jb = t - (NT - 4);
;             const bool need = jb <= wq;
;             if (late) { if (have) pv(o, vp0 + ((t - 1) & 3) * VSLOTB, pw0, pw1, pw2, pw3);
;                         have = false; if (need) qkt(p0, p1, kp0 + (t & 3) * KSLOTB, qr, negm); }
.LBB13_1743:
	s_min_u32 s84, s80, s5
	s_add_i32 s88, s80, -1
	s_min_u32 s92, s88, s5
	s_and_b32 s88, s84, 3
	s_and_b64 vcc, exec, s[90:91]
	s_cbranch_vccnz .Lat1_lw
	s_setprio 2
	s_waitcnt vmcnt(3) lgkmcnt(0)
	s_branch .Lat1_lwd

; __device__ __forceinline__ int lane_id() { int l; asm volatile("v_mbcnt_lo_u32_b32 %0, -1, 0\n\tv_mbcnt_hi_u32_b32 %0, -1, %0" : "=v"(l)); return l; }
; #define LAS __attribute__((address_space(3)))
; __device__ __forceinline__ void xb_add_l2(unsigned* p, unsigned v) { (void)__hip_atomic_fetch_add(p, v, __ATOMIC_RELAXED, __HIP_MEMORY_SCOPE_WORKGROUP); }
; __device__ __forceinline__ unsigned xb_ld_l2(unsigned* p) { unsigned v; const unsigned z = 0u; asm volatile("global_atomic_add %0, %1, %2, off sc0\n\ts_waitcnt vmcnt(0)" : "=v"(v) : "v"(p), "v"(z) : "memory"); return v; }
; __device__ __forceinline__ unsigned xb_xcc_id() { return (unsigned)__builtin_amdgcn_s_getreg((3 << 11) | 20) & 0xFu; }
; #define XB_SPIN(cond, bar) do { unsigned _sp = 0; while (cond) { __builtin_amdgcn_s_sleep(1); \
;     if ((++_sp & 255u) == 0u) { if (xb_ld(&(bar)[XB_TMO])) break; if (_sp > XB_SPIN_CAP) { atomicAdd(&(bar)[XB_TMO], 1u); break; } } } } while (0)
; #define MK_SEAM_L(k) do { if (MK_IN_(k) && MK_IN_((k) + 1)) { MK_BAR(); if (__builtin_amdgcn_readfirstlane((int)MISC[15]) != 0) xcd_local_barrier(bar.bar, bar.st, wid0); else xcd_barrier(bar, wid0); } } while (0)
; __device__ __forceinline__ void xcd_local_barrier(unsigned* bar, volatile LAS unsigned* st, int wid0) {
;     asm volatile("s_waitcnt vmcnt(0)" ::: "memory");
;     __syncthreads();
;     if (wid0 == 0 && lane_id() == 0) {
;         unsigned zo = 0; asm volatile("" : "+s"(zo));
;         unsigned* cnt = bar + zo + XB_LCNT2(xb_xcc_id());
;         const unsigned e = st[6] + 1u; st[6] = e; const unsigned target = e * st[4];
;         xb_add_l2(cnt, 1u);
;         XB_SPIN(xb_ld_l2(cnt) < target, bar);
;         __builtin_amdgcn_fence(__ATOMIC_ACQUIRE, "agent");
;         asm volatile("s_waitcnt vmcnt(0)" ::: "memory");
;     }
;     __syncthreads();
; }
; template <int l>
; __device__ __forceinline__ void layer_phases(const Args& args, LAS unsigned char* L, volatile LAS unsigned* MISC, int wid0, int lo, int hi) {
;     ...
;     MK_SEAM_L(P + 3);
.LBB13_1813:
	s_setprio 0
	s_cmp_gt_i32 s89, 13
	v_readlane_b32 s0, v238, 12
	s_cselect_b64 s[2:3], -1, 0
	v_readlane_b32 s1, v238, 13
	s_and_b64 s[0:1], s[0:1], s[2:3]
	s_and_b64 vcc, exec, s[0:1]
	v_readlane_b32 s71, v238, 9
	s_cbranch_vccz .LBB13_1893
	s_load_dword s4, s[86:87], 0xb8
	s_load_dwordx2 s[0:1], s[86:87], 0xa8
	s_getreg_b32 s22, hwreg(HW_REG_XCC_ID, 0, 4)
	s_waitcnt lgkmcnt(0)
	s_mulk_i32 s4, 0xd80
	s_ashr_i32 s5, s4, 31
	s_lshl_b64 s[4:5], s[4:5], 2
	s_add_u32 s0, s0, s4
	s_addc_u32 s1, s1, s5
	s_add_u32 s4, s0, 0x4000
	s_addc_u32 s5, s1, 0
	s_add_i32 s0, 0, 0x2117c
	v_mov_b32_e32 v0, s0
	ds_read_b32 v0, v0
	s_waitcnt lgkmcnt(0)
	v_readfirstlane_b32 s0, v0
	s_cmp_eq_u32 s0, 0
	s_cbranch_scc1 .LBB13_1829
	s_waitcnt vmcnt(0)
	v_readlane_b32 s0, v238, 10
	v_readlane_b32 s1, v238, 11
	s_and_b64 vcc, exec, s[0:1]
	s_barrier
	s_cbranch_vccnz .LBB13_1836
	v_mbcnt_lo_u32_b32 v0, -1, 0
	v_mbcnt_hi_u32_b32 v0, -1, v0
	s_mov_b32 s9, 0
	v_cmp_eq_u32_e32 vcc, 0, v0
	s_and_saveexec_b64 s[0:1], vcc
	s_cbranch_execz .LBB13_1835
	s_mov_b32 s8, 0
	s_lshl_b64 s[8:9], s[8:9], 2
	s_add_u32 s8, s4, s8
	s_getreg_b32 s10, hwreg(HW_REG_XCC_ID, 0, 4)
	s_addc_u32 s9, s5, s9
	s_lshl_b32 s10, s10, 8
	s_and_b32 s10, s10, 0xf00
	s_add_u32 s8, s8, s10
	s_addc_u32 s9, s9, 0
	s_add_u32 s8, s8, 0xb200
	s_addc_u32 s9, s9, 0
	s_add_i32 s10, 0, 0x21178
	v_mov_b32_e32 v1, s10
	ds_read_b32 v0, v1
	s_add_i32 s10, 0, 0x21170
	s_mov_b64 s[6:7], exec
	s_waitcnt vmcnt(0)
	v_mbcnt_lo_u32_b32 v2, s6, 0
	v_mbcnt_hi_u32_b32 v2, s7, v2
	s_waitcnt lgkmcnt(0)
	v_add_u32_e32 v0, 1, v0
	ds_write_b32 v1, v0
	v_mov_b32_e32 v1, s10
	ds_read_b32 v1, v1
	s_mov_b32 s23, 1
	v_cmp_eq_u32_e32 vcc, 0, v2
	s_and_saveexec_b64 s[10:11], vcc
	s_cbranch_execz .LBB13_1819
	s_bcnt1_i32_b64 s6, s[6:7]
	v_mov_b32_e32 v2, 0
	v_mov_b32_e32 v3, s6
	global_atomic_add v2, v3, s[8:9]
